# nsa top-k loop: both key compares issued before the scalar popcounts (one VALU->SALU wait per bit)
# speedup vs baseline: 1.0087x; 1.0087x over previous
.LBB0_1457:
	s_lshl_b64 s[74:75], 1, s70
	s_or_b64 s[74:75], s[74:75], s[68:69]
	v_cmp_le_u64_e64 s[88:89], s[74:75], v[56:57]
	v_cmp_le_u64_e32 vcc, s[74:75], v[58:59]
	s_bcnt1_i32_b64 s76, s[88:89]
	s_bcnt1_i32_b64 s77, vcc
	s_add_i32 s77, s77, s76
	s_cmp_gt_u32 s77, 15
	s_cselect_b32 s69, s75, s69
	s_cselect_b32 s68, s74, s68
	s_cmp_eq_u32 s77, 16
	s_cbranch_scc1 .Ltopk_done
	s_add_i32 s70, s70, -1
	s_cmp_lt_i32 s70, 0
	s_cbranch_scc0 .LBB0_1457
